# spatial phase epilogue: v_permlane16_swap merges a lane's two 8-byte pieces so each store instruction writes 64 contiguous bytes per row (4 dwordx4 instead of 8 dwordx2)
# speedup vs baseline: 1.0143x; 1.0043x over previous
; #define LAS __attribute__((address_space(3)))
; __device__ __forceinline__ int tid_opaque() { int t = threadIdx.x; asm volatile("" : "+v"(t)); return t; }
; __device__ __forceinline__ int sgpr_opaque(int x) { asm volatile("" : "+s"(x)); return x; }
; #define INP(i) ((const float*)ldp(T, (i)))
; __device__ __forceinline__ void spatial_phase(const PT& T, int a, LAS unsigned char* lds, int vc) {
;     const int tid = tid_opaque(), lane = tid & 63, wid = __builtin_amdgcn_readfirstlane(tid >> 6), fr = lane & 15, fq = lane >> 4;
;     const bf16_t* __restrict__ Z = (const bf16_t*)((unsigned char*)OUTP); bf16_t* __restrict__ Y = (bf16_t*)(WSP + WS_T2);
;     const float* __restrict__ vst = (const float*)(WSP + WS_VST + (size_t)a * MiB);
;     const float* __restrict__ gv = INP(5) + a * D; const float* __restrict__ bs = INP(7) + a * D;
;     const bf16_t* __restrict__ Wm = (const bf16_t*)(WSP + WS_W) + WO_A_S0 + (size_t)a * WO_A_STRIDE;
;     constexpr int LDW = 136;
;     LAS bf16_t* sW = (LAS bf16_t*)lds; LAS bf16_t* sV = (LAS bf16_t*)(lds + 128 * LDW * 2);
;     const int R8 = sgpr_opaque(gridDim.x) >> 3, vx = sgpr_opaque(vc) & 7, vr = sgpr_opaque(vc) >> 3;
;     const int wi = wid >> 2, wc = wid & 3, ib = wi * 64, cb = wc * 32;
;     const int jq = tid >> 4, c8 = (tid & 15) * 8;
;     for (int ti = vr; ti < 256; ti += R8) {
;         const int t = 256 * vx + ti, nb = t >> 3, g = t & 7;
;         u32x4 wreg[4], vreg[4]; f32x4 p1[4], p2[4];
; #pragma unroll
;         for (int q = 0; q < 4; ++q) { const int j = jq + 32 * q; const size_t row = (size_t)nb * 128 + j;
;             wreg[q] = *(const u32x4*)(Wm + (size_t)g * 16384 + j * 128 + c8);
;             vreg[q] = *(const u32x4*)(Z + row * 2048 + 1024 + g * 128 + c8);
;             p1[q] = *(const f32x4*)(vst + 8 * row); p2[q] = *(const f32x4*)(vst + 8 * row + 4); }
;         const f32x4 g0 = *(const f32x4*)(gv + g * 128 + c8), g1 = *(const f32x4*)(gv + g * 128 + c8 + 4);
;     ...
;             for (int n = 0; n < 2; ++n) { const int c = g * 128 + cb + 16 * n + 4 * fq; const u32x2 u2 = uu[mt][n];
.LBB0_795:
	v_readlane_b32 s0, v254, 8
	v_mov_b32_e32 v0, v220
	v_readlane_b32 s4, v254, 13
	v_mov_b32_e32 v2, s0
	s_waitcnt lgkmcnt(0)
	ds_read2_b64 v[2:5], v2 offset1:1
	v_readlane_b32 s0, v254, 12
	s_mov_b32 s15, s68
	v_readfirstlane_b32 s10, v0
	v_mov_b32_e32 v6, s0
	ds_read_b64 v[6:7], v6
	s_waitcnt lgkmcnt(0)
	v_readfirstlane_b32 s0, v2
	v_mov_b32_e32 v2, s4
	v_readfirstlane_b32 s1, v3
	ds_read_b64 v[2:3], v2
	v_readlane_b32 s4, v254, 22
	s_mov_b32 s18, s4
	s_ashr_i32 s4, s4, 3
	v_readfirstlane_b32 s16, v5
	v_readfirstlane_b32 s19, v4
	v_readfirstlane_b32 s11, v7
	v_readfirstlane_b32 s17, v6
	s_waitcnt lgkmcnt(0)
	v_readfirstlane_b32 s9, v3
	s_cmpk_gt_i32 s4, 0xff
	v_readfirstlane_b32 s8, v2
	s_cbranch_scc1 .LBB0_800
	s_add_u32 s5, s19, 0x15000000
	v_readlane_b32 s6, v254, 27
	s_addc_u32 s14, s16, 0
	v_readlane_b32 s7, v254, 28
	s_mov_b32 s28, s6
	s_ashr_i32 s29, s6, 31
	s_lshl_b64 s[6:7], s[28:29], 20
	s_add_u32 s6, s19, s6
	s_addc_u32 s7, s16, s7
	s_add_u32 s6, s6, 0x19500000
	s_addc_u32 s7, s7, 0
	s_lshl_b32 s20, s28, 10
	s_ashr_i32 s21, s20, 31
	s_lshl_b64 s[20:21], s[20:21], 2
	s_add_u32 s8, s8, s20
	s_addc_u32 s9, s9, s21
	s_lshr_b32 s22, s10, 1
	s_ashr_i32 s25, s10, 2
	s_ashr_i32 s15, s15, 3
	s_and_b32 s24, s22, 0x60
	s_and_b32 s26, s25, 0xffffffc0
	s_mul_i32 s22, s28, 0x640000
	s_mul_hi_i32 s23, s28, 0x640000
	s_add_u32 s22, s19, s22
	s_addc_u32 s23, s16, s23
	s_add_u32 s20, s17, s20
	s_addc_u32 s21, s11, s21
	s_lshl_b32 s11, s18, 8
	v_lshlrev_b32_e32 v2, 3, v0
	s_and_b32 s16, s11, 0x700
	v_ashrrev_i32_e32 v34, 4, v0
	v_and_b32_e32 v2, 0x78, v2
	s_cmpk_lt_u32 s10, 0x100
	s_movk_i32 s11, 0x110
	v_bfe_u32 v3, v0, 4, 2
	v_and_b32_e32 v12, 15, v0
	v_lshlrev_b32_e32 v0, 1, v2
	s_cselect_b32 s17, 2, 4
	v_mul_lo_u32 v6, v34, s11
	s_and_b32 s10, s10, 0xc0
	v_lshl_add_u64 v[4:5], s[22:23], 0, v[0:1]
	v_add3_u32 v91, 0, v0, v6
	v_mov_b32_e32 v0, s10
	s_movk_i32 s10, 0x880
	v_or_b32_e32 v40, s26, v12
	v_mad_u32_u24 v0, v3, s10, v0
	v_ashrrev_i32_e32 v41, 31, v40
	v_lshl_or_b32 v0, v12, 1, v0
	v_readlane_b32 s10, v254, 14
	v_lshlrev_b64 v[56:57], 12, v[40:41]
	v_lshlrev_b64 v[64:65], 11, v[40:41]
	v_add_u32_e32 v41, s10, v0
	v_and_b32_e32 v217, 0xc0, v220
	v_lshl_or_b32 v217, v12, 1, v217
	v_lshl_add_u32 v217, v3, 5, v217
	v_and_b32_e32 v218, 0xff, v217
	v_add_u32_e32 v217, 32, v217
	v_and_b32_e32 v217, 0xff, v217
	v_mul_u32_u24_e32 v216, 0x880, v3
	v_add_u32_e32 v216, s10, v216
	v_add_u32_e32 v215, v216, v218
	v_add_u32_e32 v216, v216, v217
	v_bfe_u32 v217, v34, 3, 2
	v_lshlrev_b32_e32 v218, 1, v2
	v_lshl_add_u32 v217, v217, 5, v218
	v_and_b32_e32 v217, 0xff, v217
	v_add_u32_e32 v214, v6, v217
	s_lshr_b32 s10, s25, 6
	s_mov_b64 s[18:19], 0xa00000
	s_mulk_i32 s10, 0x4400
	v_lshl_add_u64 v[36:37], v[4:5], 0, s[18:19]
	v_lshlrev_b32_e32 v4, 2, v2
	v_mov_b32_e32 v5, v1
	v_add_u32_e32 v44, 32, v34
	v_add_u32_e32 v48, 64, v34
	v_add_u32_e32 v52, 0x60, v34
	v_or_b32_e32 v6, 16, v40
	v_or_b32_e32 v8, 32, v40
	v_or_b32_e32 v10, 48, v40
	v_mov_b32_e32 v0, s10
	v_lshl_add_u64 v[38:39], s[20:21], 0, v[4:5]
	v_lshlrev_b32_e32 v4, 2, v3
	v_lshlrev_b32_e32 v5, 4, v3
	v_lshlrev_b32_e32 v42, 7, v34
	v_lshlrev_b32_e32 v46, 7, v44
	v_lshlrev_b32_e32 v50, 7, v48
	v_lshlrev_b32_e32 v54, 7, v52
	v_ashrrev_i32_e32 v7, 31, v6
	v_ashrrev_i32_e32 v9, 31, v8
	v_ashrrev_i32_e32 v11, 31, v10
	v_mad_u32_u24 v0, v12, s11, v0
	v_or_b32_e32 v90, s24, v4
	v_and_b32_e32 v90, 1, v3
	v_lshrrev_b32_e32 v218, 1, v3
	v_lshlrev_b32_e32 v90, 4, v90
	v_lshl_or_b32 v90, v218, 3, v90
	v_or_b32_e32 v90, s24, v90
	v_ashrrev_i32_e32 v35, 31, v34
	v_ashrrev_i32_e32 v43, 31, v42
	v_ashrrev_i32_e32 v45, 31, v44
	v_ashrrev_i32_e32 v47, 31, v46
	v_ashrrev_i32_e32 v49, 31, v48
	v_ashrrev_i32_e32 v51, 31, v50
	v_ashrrev_i32_e32 v53, 31, v52
	v_ashrrev_i32_e32 v55, 31, v54
	v_lshlrev_b64 v[58:59], 12, v[6:7]
	v_lshlrev_b64 v[60:61], 12, v[8:9]
	v_lshlrev_b64 v[62:63], 12, v[10:11]
	v_lshlrev_b64 v[66:67], 11, v[6:7]
	v_lshlrev_b64 v[68:69], 11, v[8:9]
	v_lshlrev_b64 v[70:71], 11, v[10:11]
	v_add3_u32 v92, v0, v5, 0
	v_lshlrev_b32_e32 v0, 1, v2
	s_lshl_b32 s18, s24, 1
	v_lshlrev_b32_e32 v72, 1, v4
	s_add_i32 s10, s4, s16
	s_ashr_i32 s10, s10, 3
	s_ashr_i32 s11, s10, 31
	s_lshl_b64 s[20:21], s[10:11], 7
	v_lshl_add_u64 v[120:121], s[20:21], 0, v[34:35]
	v_lshlrev_b64 v[122:123], 5, v[120:121]
	v_lshl_add_u64 v[122:123], s[6:7], 0, v[122:123]
	global_load_dwordx4 v[140:143], v[122:123], off
	global_load_dwordx4 v[144:147], v[122:123], off offset:16
	s_and_b32 s19, s4, 7
	s_lshl_b32 s46, s19, 15
	v_lshlrev_b64 v[120:121], 12, v[120:121]
	v_lshl_add_u64 v[124:125], v[36:37], 0, s[46:47]
	v_lshl_add_u64 v[120:121], s[0:1], 0, v[120:121]
	s_lshl_b32 s46, s19, 8
	v_lshl_add_u64 v[120:121], v[120:121], 0, s[46:47]
	v_lshl_add_u64 v[120:121], v[120:121], 0, v[0:1]
	global_load_dwordx4 v[148:151], v[120:121], off offset:2048
	s_mov_b32 s23, s47
	s_lshl_b32 s22, s19, 9
	v_lshl_add_u64 v[120:121], v[38:39], 0, s[22:23]
	global_load_dwordx4 v[128:131], v[120:121], off
	s_nop 0
	global_load_dwordx4 v[120:123], v[120:121], off offset:16
	v_lshl_add_u64 v[126:127], v[42:43], 1, v[124:125]
	v_lshl_add_u64 v[132:133], v[46:47], 1, v[124:125]
	v_lshl_add_u64 v[168:169], s[20:21], 0, v[44:45]
	global_load_dwordx4 v[152:155], v[126:127], off
	global_load_dwordx4 v[156:159], v[132:133], off
	v_lshlrev_b64 v[126:127], 5, v[168:169]
	v_lshl_add_u64 v[126:127], s[6:7], 0, v[126:127]
	global_load_dwordx4 v[160:163], v[126:127], off
	v_lshl_add_u64 v[134:135], v[50:51], 1, v[124:125]
	v_lshl_add_u64 v[124:125], v[54:55], 1, v[124:125]
	global_load_dwordx4 v[136:139], v[134:135], off
	global_load_dwordx4 v[164:167], v[126:127], off offset:16
	s_nop 0
	global_load_dwordx4 v[124:127], v[124:125], off
	v_lshlrev_b64 v[168:169], 12, v[168:169]
	v_lshl_add_u64 v[168:169], s[0:1], 0, v[168:169]
	v_lshl_add_u64 v[132:133], s[20:21], 0, v[48:49]
	v_lshl_add_u64 v[168:169], v[168:169], 0, s[46:47]
	v_lshlrev_b64 v[170:171], 12, v[132:133]
	v_lshl_add_u64 v[168:169], v[168:169], 0, v[0:1]
	v_lshl_add_u64 v[174:175], s[0:1], 0, v[170:171]
	global_load_dwordx4 v[168:171], v[168:169], off offset:2048
	v_lshl_add_u64 v[134:135], s[20:21], 0, v[52:53]
	v_lshlrev_b64 v[132:133], 5, v[132:133]
	v_lshlrev_b64 v[172:173], 12, v[134:135]
	v_lshl_add_u64 v[132:133], s[6:7], 0, v[132:133]
	v_lshl_add_u64 v[180:181], s[0:1], 0, v[172:173]
	v_lshl_add_u64 v[188:189], v[174:175], 0, s[46:47]
	global_load_dwordx4 v[172:175], v[132:133], off
	global_load_dwordx4 v[176:179], v[132:133], off offset:16
	v_lshlrev_b64 v[134:135], 5, v[134:135]
	v_lshl_add_u64 v[134:135], s[6:7], 0, v[134:135]
	v_lshl_add_u64 v[132:133], v[180:181], 0, s[46:47]
	global_load_dwordx4 v[180:183], v[134:135], off
	global_load_dwordx4 v[184:187], v[134:135], off offset:16
	v_lshl_add_u64 v[134:135], v[188:189], 0, v[0:1]
	v_lshl_add_u64 v[132:133], v[132:133], 0, v[0:1]
	global_load_dwordx4 v[188:191], v[134:135], off offset:2048
	s_nop 0
	global_load_dwordx4 v[132:135], v[132:133], off offset:2048
	s_waitcnt vmcnt(0)
; #define LAS __attribute__((address_space(3)))
; __device__ __forceinline__ unsigned pk2(float lo, float hi) { return pg8::cvt_pk_bf16(lo, hi); }
; __device__ __forceinline__ void spatial_phase(const PT& T, int a, LAS unsigned char* lds, int vc) {
;     ...
;         for (int q = 0; q < 4; ++q) { const int j = jq + 32 * q;
;             const float s1 = (p1[q].x + p1[q].y) + (p1[q].z + p1[q].w), s2 = (p2[q].x + p2[q].y) + (p2[q].z + p2[q].w);
;             const float mu = s1 * (1.0f / D); float var = s2 * (1.0f / D) - mu * mu; var = var > 0.f ? var : 0.f; const float rs = __builtin_amdgcn_rsqf(var + EPS);
;             const u32x4 raw = vreg[q];
;             u32x4 o; o.x = pk2((bflo(raw.x) - mu) * rs * g0.x, (bfhi(raw.x) - mu) * rs * g0.y); o.y = pk2((bflo(raw.y) - mu) * rs * g0.z, (bfhi(raw.y) - mu) * rs * g0.w);
;             o.z = pk2((bflo(raw.z) - mu) * rs * g1.x, (bfhi(raw.z) - mu) * rs * g1.y); o.w = pk2((bflo(raw.w) - mu) * rs * g1.z, (bfhi(raw.w) - mu) * rs * g1.w);
;             *(LAS u32x4*)(sV + j * LDW + c8) = o; *(LAS u32x4*)(sW + j * LDW + c8) = wreg[q]; }
.LBB0_797:
	s_add_i32 s10, s4, s16
	s_ashr_i32 s10, s10, 3
	s_ashr_i32 s11, s10, 31
	s_and_b32 s19, s4, 7
	s_lshl_b32 s46, s19, 8
	s_mov_b32 s20, 0x3a800000
	s_lshl_b32 s19, s19, 7
	s_waitcnt vmcnt(4) lgkmcnt(0)
	v_mov_b32_e32 v192, v141
	v_mov_b32_e32 v193, v142
	v_mov_b32_e32 v141, v143
	v_pk_add_f32 v[140:141], v[192:193], v[140:141]
	v_add_f32_e32 v142, v144, v145
	v_add_f32_e32 v144, v146, v147
	v_mov_b32_e32 v143, v140
	v_mov_b32_e32 v145, v141
	v_pk_add_f32 v[140:141], v[142:143], v[144:145]
	v_lshlrev_b32_e32 v146, 16, v148
	v_pk_mul_f32 v[142:143], v[140:141], s[20:21] op_sel_hi:[1,0]
	v_and_b32_e32 v147, 0xffff0000, v148
	v_fma_f32 v140, -v143, v143, v142
	v_max_f32_e32 v140, 0, v140
	v_add_f32_e32 v140, 0x358637bd, v140
	v_rsq_f32_e32 v145, v140
	v_lshlrev_b32_e32 v148, 16, v149
	v_lshlrev_b32_e32 v73, 16, v150
	v_and_b32_e32 v149, 0xffff0000, v149
	v_and_b32_e32 v150, 0xffff0000, v150
	v_sub_f32_e32 v141, v146, v143
	v_sub_f32_e32 v142, v147, v143
	v_sub_f32_e32 v144, v148, v143
	v_sub_f32_e32 v146, v73, v143
	v_sub_f32_e32 v140, v149, v143
	v_sub_f32_e32 v147, v150, v143
	v_mul_f32_e32 v141, v141, v145
	v_mul_f32_e32 v142, v142, v145
	v_mul_f32_e32 v144, v144, v145
	v_mul_f32_e32 v146, v146, v145
	v_mul_f32_e32 v140, v140, v145
	v_mul_f32_e32 v147, v147, v145
	v_mul_f32_e32 v141, v141, v128
	v_mul_f32_e32 v142, v142, v129
	v_mul_f32_e32 v144, v144, v130
	v_mul_f32_e32 v146, v146, v120
	v_mul_f32_e32 v148, v140, v131
	v_mul_f32_e32 v147, v147, v121
	v_cvt_pk_bf16_f32 v140, v141, v142
	v_cvt_pk_bf16_f32 v141, v144, v148
	v_cvt_pk_bf16_f32 v142, v146, v147
	v_lshlrev_b32_e32 v144, 16, v151
	v_and_b32_e32 v146, 0xffff0000, v151
	v_sub_f32_e32 v144, v144, v143
	v_sub_f32_e32 v143, v146, v143
	v_mul_f32_e32 v143, v143, v145
	v_mul_f32_e32 v144, v144, v145
	v_mul_f32_e32 v143, v143, v123
	v_mul_f32_e32 v144, v144, v122
	v_cvt_pk_bf16_f32 v143, v144, v143
	ds_write_b128 v214, v[140:143] offset:34816
	v_mov_b32_e32 v140, v161
	v_mov_b32_e32 v141, v162
	v_mov_b32_e32 v161, v163
	v_pk_add_f32 v[140:141], v[140:141], v[160:161]
	v_add_f32_e32 v142, v164, v165
	v_add_f32_e32 v144, v166, v167
	v_mov_b32_e32 v143, v140
	v_mov_b32_e32 v145, v141
	v_pk_add_f32 v[140:141], v[142:143], v[144:145]
	ds_write_b128 v91, v[152:155]
	v_pk_mul_f32 v[142:143], v[140:141], s[20:21] op_sel_hi:[1,0]
	v_and_b32_e32 v141, 0xffff0000, v168
	v_fma_f32 v140, -v143, v143, v142
	v_max_f32_e32 v140, 0, v140
	v_add_f32_e32 v140, 0x358637bd, v140
	v_rsq_f32_e32 v144, v140
	v_lshlrev_b32_e32 v140, 16, v168
	v_sub_f32_e32 v140, v140, v143
	v_sub_f32_e32 v141, v141, v143
	v_mul_f32_e32 v140, v140, v144
	v_mul_f32_e32 v141, v141, v144
	v_mul_f32_e32 v140, v128, v140
	v_mul_f32_e32 v141, v129, v141
	v_cvt_pk_bf16_f32 v140, v140, v141
	v_lshlrev_b32_e32 v141, 16, v169
	v_and_b32_e32 v142, 0xffff0000, v169
	v_sub_f32_e32 v141, v141, v143
	v_sub_f32_e32 v142, v142, v143
	v_mul_f32_e32 v141, v141, v144
	v_mul_f32_e32 v142, v142, v144
	v_mul_f32_e32 v141, v130, v141
	v_mul_f32_e32 v142, v131, v142
	v_cvt_pk_bf16_f32 v141, v141, v142
	v_lshlrev_b32_e32 v142, 16, v170
	v_and_b32_e32 v145, 0xffff0000, v170
	v_sub_f32_e32 v142, v142, v143
	v_sub_f32_e32 v145, v145, v143
	v_mul_f32_e32 v142, v142, v144
	v_mul_f32_e32 v145, v145, v144
	v_mul_f32_e32 v142, v142, v120
	v_mul_f32_e32 v145, v145, v121
	v_cvt_pk_bf16_f32 v142, v142, v145
	v_lshlrev_b32_e32 v145, 16, v171
	v_and_b32_e32 v146, 0xffff0000, v171
	v_sub_f32_e32 v145, v145, v143
	v_sub_f32_e32 v143, v146, v143
	v_mul_f32_e32 v143, v143, v144
	v_mul_f32_e32 v145, v145, v144
	v_mul_f32_e32 v143, v143, v123
	v_mul_f32_e32 v145, v145, v122
	v_cvt_pk_bf16_f32 v143, v145, v143
	ds_write_b128 v214, v[140:143] offset:43520
	v_mov_b32_e32 v140, v173
	v_mov_b32_e32 v141, v174
	v_mov_b32_e32 v173, v175
	v_pk_add_f32 v[140:141], v[140:141], v[172:173]
	v_add_f32_e32 v142, v176, v177
	v_add_f32_e32 v144, v178, v179
	v_mov_b32_e32 v143, v140
	v_mov_b32_e32 v145, v141
	v_pk_add_f32 v[140:141], v[142:143], v[144:145]
	ds_write_b128 v91, v[156:159] offset:8704
	v_pk_mul_f32 v[142:143], v[140:141], s[20:21] op_sel_hi:[1,0]
	v_and_b32_e32 v141, 0xffff0000, v188
	v_fma_f32 v140, -v143, v143, v142
	v_max_f32_e32 v140, 0, v140
	v_add_f32_e32 v140, 0x358637bd, v140
	v_rsq_f32_e32 v144, v140
	v_lshlrev_b32_e32 v140, 16, v188
	v_sub_f32_e32 v140, v140, v143
	v_sub_f32_e32 v141, v141, v143
	v_mul_f32_e32 v140, v140, v144
	v_mul_f32_e32 v141, v141, v144
	v_mul_f32_e32 v140, v128, v140
	v_mul_f32_e32 v141, v129, v141
	v_cvt_pk_bf16_f32 v140, v140, v141
	v_lshlrev_b32_e32 v141, 16, v189
	v_and_b32_e32 v142, 0xffff0000, v189
	v_sub_f32_e32 v141, v141, v143
	v_sub_f32_e32 v142, v142, v143
	v_mul_f32_e32 v141, v141, v144
	v_mul_f32_e32 v142, v142, v144
	v_mul_f32_e32 v141, v130, v141
	v_mul_f32_e32 v142, v131, v142
	v_cvt_pk_bf16_f32 v141, v141, v142
	v_lshlrev_b32_e32 v142, 16, v190
	v_and_b32_e32 v145, 0xffff0000, v190
	v_sub_f32_e32 v142, v142, v143
	v_sub_f32_e32 v145, v145, v143
	v_mul_f32_e32 v142, v142, v144
	v_mul_f32_e32 v145, v145, v144
	v_mul_f32_e32 v142, v120, v142
	v_mul_f32_e32 v145, v121, v145
	v_cvt_pk_bf16_f32 v142, v142, v145
	v_lshlrev_b32_e32 v145, 16, v191
	v_and_b32_e32 v146, 0xffff0000, v191
	v_sub_f32_e32 v145, v145, v143
	v_sub_f32_e32 v143, v146, v143
	v_mul_f32_e32 v143, v143, v144
	v_mul_f32_e32 v145, v145, v144
	v_mul_f32_e32 v143, v123, v143
	v_mul_f32_e32 v145, v122, v145
	v_cvt_pk_bf16_f32 v143, v145, v143
	ds_write_b128 v214, v[140:143] offset:52224
	v_mov_b32_e32 v140, v181
	v_mov_b32_e32 v141, v182
	v_mov_b32_e32 v181, v183
	v_pk_add_f32 v[140:141], v[140:141], v[180:181]
	v_add_f32_e32 v142, v184, v185
; #define LAS __attribute__((address_space(3)))
; __device__ __forceinline__ unsigned pk2(float lo, float hi) { return pg8::cvt_pk_bf16(lo, hi); }
; __device__ __forceinline__ void spatial_phase(const PT& T, int a, LAS unsigned char* lds, int vc) {
;     ...
;         for (int q = 0; q < 4; ++q) { const int j = jq + 32 * q; const size_t row = (size_t)nb * 128 + j;
;             wreg[q] = *(const u32x4*)(Wm + (size_t)g * 16384 + j * 128 + c8);
;             vreg[q] = *(const u32x4*)(Z + row * 2048 + 1024 + g * 128 + c8);
;             p1[q] = *(const f32x4*)(vst + 8 * row); p2[q] = *(const f32x4*)(vst + 8 * row + 4); }
;         const f32x4 g0 = *(const f32x4*)(gv + g * 128 + c8), g1 = *(const f32x4*)(gv + g * 128 + c8 + 4);
;     ...
;             const float s1 = (p1[q].x + p1[q].y) + (p1[q].z + p1[q].w), s2 = (p2[q].x + p2[q].y) + (p2[q].z + p2[q].w);
;             const float mu = s1 * (1.0f / D); float var = s2 * (1.0f / D) - mu * mu; var = var > 0.f ? var : 0.f; const float rs = __builtin_amdgcn_rsqf(var + EPS);
;             const u32x4 raw = vreg[q];
;             u32x4 o; o.x = pk2((bflo(raw.x) - mu) * rs * g0.x, (bfhi(raw.x) - mu) * rs * g0.y); o.y = pk2((bflo(raw.y) - mu) * rs * g0.z, (bfhi(raw.y) - mu) * rs * g0.w);
;             o.z = pk2((bflo(raw.z) - mu) * rs * g1.x, (bfhi(raw.z) - mu) * rs * g1.y); o.w = pk2((bflo(raw.w) - mu) * rs * g1.z, (bfhi(raw.w) - mu) * rs * g1.w);
;             *(LAS u32x4*)(sV + j * LDW + c8) = o; *(LAS u32x4*)(sW + j * LDW + c8) = wreg[q]; }
;         u32x2 uu[4][2]; float bsv[4];
; #pragma unroll
;         for (int mt = 0; mt < 4; ++mt) { const int i = ib + 16 * mt + fr; bsv[mt] = bs[g * 128 + i];
; #pragma unroll
;             for (int n = 0; n < 2; ++n) uu[mt][n] = *(const u32x2*)(Z + ((size_t)nb * 128 + i) * 2048 + g * 128 + cb + 16 * n + 4 * fq); }
;         __syncthreads();
;         f32x4 acc[4][2];
; #pragma unroll
;         for (int mt = 0; mt < 4; ++mt)
; #pragma unroll
;             for (int n = 0; n < 2; ++n) acc[mt][n] = (f32x4){0.f, 0.f, 0.f, 0.f};
	v_add_f32_e32 v144, v186, v187
	v_mov_b32_e32 v143, v140
	v_mov_b32_e32 v145, v141
	v_pk_add_f32 v[140:141], v[142:143], v[144:145]
	ds_write_b128 v91, v[136:139] offset:17408
	v_pk_mul_f32 v[140:141], v[140:141], s[20:21] op_sel_hi:[1,0]
	v_lshlrev_b32_e32 v136, 16, v132
	v_fma_f32 v140, -v141, v141, v140
	v_max_f32_e32 v140, 0, v140
	v_add_f32_e32 v140, 0x358637bd, v140
	v_rsq_f32_e32 v140, v140
	v_and_b32_e32 v132, 0xffff0000, v132
	v_sub_f32_e32 v136, v136, v141
	v_sub_f32_e32 v132, v132, v141
	v_mul_f32_e32 v136, v136, v140
	v_mul_f32_e32 v132, v132, v140
	v_mul_f32_e32 v128, v128, v136
	v_mul_f32_e32 v129, v129, v132
	v_cvt_pk_bf16_f32 v128, v128, v129
	v_lshlrev_b32_e32 v129, 16, v133
	v_sub_f32_e32 v129, v129, v141
	v_mul_f32_e32 v129, v129, v140
	v_mul_f32_e32 v129, v130, v129
	v_and_b32_e32 v130, 0xffff0000, v133
	v_sub_f32_e32 v130, v130, v141
	v_mul_f32_e32 v130, v130, v140
	v_mul_f32_e32 v130, v131, v130
	v_cvt_pk_bf16_f32 v129, v129, v130
	v_lshlrev_b32_e32 v130, 16, v134
	v_sub_f32_e32 v130, v130, v141
	v_mul_f32_e32 v130, v130, v140
	v_mul_f32_e32 v120, v120, v130
	v_and_b32_e32 v130, 0xffff0000, v134
	v_sub_f32_e32 v130, v130, v141
	s_lshl_b64 s[20:21], s[10:11], 19
	v_mul_f32_e32 v130, v130, v140
	s_add_u32 s20, s0, s20
	v_mul_f32_e32 v121, v121, v130
	s_addc_u32 s21, s1, s21
	v_cvt_pk_bf16_f32 v130, v120, v121
	v_lshlrev_b32_e32 v120, 16, v135
	v_and_b32_e32 v121, 0xffff0000, v135
	s_add_u32 s20, s20, s46
	v_sub_f32_e32 v120, v120, v141
	v_sub_f32_e32 v121, v121, v141
	s_addc_u32 s21, s21, 0
	v_mul_f32_e32 v120, v120, v140
	v_mul_f32_e32 v121, v121, v140
	s_add_u32 s20, s20, s18
	v_mul_f32_e32 v120, v122, v120
	v_mul_f32_e32 v121, v123, v121
	s_addc_u32 s21, s21, 0
	v_mov_b32_e32 v73, v1
	v_cvt_pk_bf16_f32 v131, v120, v121
	ds_write_b128 v214, v[128:131] offset:60928
	ds_write_b128 v91, v[124:127] offset:26112
	v_lshl_add_u64 v[2:3], s[20:21], 0, v[72:73]
	v_add_u32_e32 v4, s19, v40
	v_ashrrev_i32_e32 v5, 31, v4
	v_lshl_add_u64 v[6:7], v[2:3], 0, v[56:57]
	v_lshl_add_u64 v[4:5], v[4:5], 2, s[8:9]
	v_lshl_add_u64 v[8:9], v[2:3], 0, v[58:59]
	global_load_dwordx2 v[88:89], v[6:7], off
	global_load_dwordx2 v[86:87], v[6:7], off offset:32
	global_load_dwordx2 v[84:85], v[8:9], off
	global_load_dwordx2 v[82:83], v[8:9], off offset:32
	v_lshl_add_u64 v[6:7], v[2:3], 0, v[60:61]
	global_load_dword v95, v[4:5], off
	global_load_dword v94, v[4:5], off offset:64
	global_load_dword v93, v[4:5], off offset:128
	global_load_dword v73, v[4:5], off offset:192
	v_lshl_add_u64 v[2:3], v[2:3], 0, v[62:63]
	global_load_dwordx2 v[80:81], v[6:7], off
	global_load_dwordx2 v[78:79], v[6:7], off offset:32
	global_load_dwordx2 v[76:77], v[2:3], off
	global_load_dwordx2 v[74:75], v[2:3], off offset:32
	v_mov_b32_e32 v2, 0
	v_mov_b32_e32 v96, v92
	v_mov_b32_e32 v97, v215
	v_mov_b32_e32 v217, v216
	s_mov_b32 s20, s17
	v_mov_b32_e32 v3, v2
	v_mov_b32_e32 v4, v2
	v_mov_b32_e32 v5, v2
	v_mov_b32_e32 v6, v2
	v_mov_b32_e32 v7, v2
	v_mov_b32_e32 v8, v2
	v_mov_b32_e32 v9, v2
	v_mov_b32_e32 v10, v2
	v_mov_b32_e32 v11, v2
	v_mov_b32_e32 v12, v2
	v_mov_b32_e32 v13, v2
	v_mov_b32_e32 v14, v2
	v_mov_b32_e32 v15, v2
	v_mov_b32_e32 v16, v2
	v_mov_b32_e32 v17, v2
	v_mov_b32_e32 v18, v2
	v_mov_b32_e32 v19, v2
	v_mov_b32_e32 v20, v2
	v_mov_b32_e32 v21, v2
	v_mov_b32_e32 v22, v2
	v_mov_b32_e32 v23, v2
	v_mov_b32_e32 v24, v2
	v_mov_b32_e32 v25, v2
	v_mov_b32_e32 v26, v2
	v_mov_b32_e32 v27, v2
	v_mov_b32_e32 v28, v2
	v_mov_b32_e32 v29, v2
	v_mov_b32_e32 v30, v2
	v_mov_b32_e32 v31, v2
	v_mov_b32_e32 v32, v2
	v_mov_b32_e32 v33, v2
	s_waitcnt lgkmcnt(0)
	s_barrier
	s_add_i32 s24, s4, s15
	s_cmpk_gt_i32 s24, 0xff
	s_cbranch_scc1 .Lsp_nopf
	s_mov_b32 vcc_hi, 0
	s_add_i32 s26, s24, s16
	s_ashr_i32 s28, s26, 3
	s_ashr_i32 s29, s28, 31
	s_lshl_b64 s[28:29], s[28:29], 7
	v_lshl_add_u64 v[120:121], s[28:29], 0, v[34:35]
	v_lshlrev_b64 v[122:123], 5, v[120:121]
	v_lshl_add_u64 v[122:123], s[6:7], 0, v[122:123]
	global_load_dwordx4 v[140:143], v[122:123], off
	global_load_dwordx4 v[144:147], v[122:123], off offset:16
	s_and_b32 s25, s24, 7
	s_lshl_b32 vcc_lo, s25, 15
	v_lshlrev_b64 v[120:121], 12, v[120:121]
	v_lshl_add_u64 v[124:125], v[36:37], 0, vcc
	v_lshl_add_u64 v[120:121], s[0:1], 0, v[120:121]
	s_lshl_b32 vcc_lo, s25, 8
	v_lshl_add_u64 v[120:121], v[120:121], 0, vcc
	v_lshl_add_u64 v[120:121], v[120:121], 0, v[0:1]
	global_load_dwordx4 v[148:151], v[120:121], off offset:2048
	s_lshl_b32 vcc_lo, s25, 9
	v_lshl_add_u64 v[120:121], v[38:39], 0, vcc
	s_lshl_b32 vcc_lo, s25, 8
	global_load_dwordx4 v[128:131], v[120:121], off
	s_nop 0
	global_load_dwordx4 v[120:123], v[120:121], off offset:16
	v_lshl_add_u64 v[126:127], v[42:43], 1, v[124:125]
	v_lshl_add_u64 v[132:133], v[46:47], 1, v[124:125]
	v_lshl_add_u64 v[168:169], s[28:29], 0, v[44:45]
	global_load_dwordx4 v[152:155], v[126:127], off
	global_load_dwordx4 v[156:159], v[132:133], off
	v_lshlrev_b64 v[126:127], 5, v[168:169]
	v_lshl_add_u64 v[126:127], s[6:7], 0, v[126:127]
	global_load_dwordx4 v[160:163], v[126:127], off
	v_lshl_add_u64 v[134:135], v[50:51], 1, v[124:125]
	v_lshl_add_u64 v[124:125], v[54:55], 1, v[124:125]
	global_load_dwordx4 v[136:139], v[134:135], off
	global_load_dwordx4 v[164:167], v[126:127], off offset:16
	s_nop 0
	global_load_dwordx4 v[124:127], v[124:125], off
	v_lshlrev_b64 v[168:169], 12, v[168:169]
	v_lshl_add_u64 v[168:169], s[0:1], 0, v[168:169]
	v_lshl_add_u64 v[132:133], s[28:29], 0, v[48:49]
	v_lshl_add_u64 v[168:169], v[168:169], 0, vcc
	v_lshlrev_b64 v[170:171], 12, v[132:133]
	v_lshl_add_u64 v[168:169], v[168:169], 0, v[0:1]
	v_lshl_add_u64 v[174:175], s[0:1], 0, v[170:171]
	global_load_dwordx4 v[168:171], v[168:169], off offset:2048
	v_lshl_add_u64 v[134:135], s[28:29], 0, v[52:53]
	v_lshlrev_b64 v[132:133], 5, v[132:133]
	v_lshlrev_b64 v[172:173], 12, v[134:135]
	v_lshl_add_u64 v[132:133], s[6:7], 0, v[132:133]
	v_lshl_add_u64 v[180:181], s[0:1], 0, v[172:173]
	v_lshl_add_u64 v[188:189], v[174:175], 0, vcc
	global_load_dwordx4 v[172:175], v[132:133], off
	global_load_dwordx4 v[176:179], v[132:133], off offset:16
	v_lshlrev_b64 v[134:135], 5, v[134:135]
	v_lshl_add_u64 v[134:135], s[6:7], 0, v[134:135]
	v_lshl_add_u64 v[132:133], v[180:181], 0, vcc
	global_load_dwordx4 v[180:183], v[134:135], off
	global_load_dwordx4 v[184:187], v[134:135], off offset:16
	v_lshl_add_u64 v[134:135], v[188:189], 0, v[0:1]
	v_lshl_add_u64 v[132:133], v[132:133], 0, v[0:1]
	global_load_dwordx4 v[188:191], v[134:135], off offset:2048
	s_nop 0
	global_load_dwordx4 v[132:135], v[132:133], off offset:2048

; __device__ __forceinline__ unsigned pk2(float lo, float hi) { return pg8::cvt_pk_bf16(lo, hi); }
; __device__ __forceinline__ void spatial_phase(const PT& T, int a, LAS unsigned char* lds, int vc) {
;     ...
; #pragma unroll
;         for (int mt = 0; mt < 4; ++mt) { const int i = ib + 16 * mt + fr; const size_t row = (size_t)nb * 128 + i;
; #pragma unroll
;             for (int n = 0; n < 2; ++n) { const int c = g * 128 + cb + 16 * n + 4 * fq; const u32x2 u2 = uu[mt][n];
;                 u32x2 o; o.x = pk2(bflo(u2.x) * (acc[mt][n][0] + bsv[mt]), bfhi(u2.x) * (acc[mt][n][1] + bsv[mt])); o.y = pk2(bflo(u2.y) * (acc[mt][n][2] + bsv[mt]), bfhi(u2.y) * (acc[mt][n][3] + bsv[mt]));
;                 *(u32x2*)(Y + row * D + c) = o; } }
;         __syncthreads();
.Lsp_epi:
	v_lshlrev_b32_e32 v99, 16, v88
	v_add_f32_e32 v30, v95, v30
	v_and_b32_e32 v88, 0xffff0000, v88
	v_add_f32_e32 v31, v95, v31
	v_mul_f32_e32 v30, v30, v99
	v_mul_f32_e32 v31, v31, v88
	s_lshl_b64 s[10:11], s[10:11], 18
	v_cvt_pk_bf16_f32 v30, v30, v31
	v_lshlrev_b32_e32 v31, 16, v89
	v_add_f32_e32 v32, v95, v32
	s_add_u32 s10, s5, s10
	v_mul_f32_e32 v31, v32, v31
	v_and_b32_e32 v32, 0xffff0000, v89
	v_add_f32_e32 v33, v95, v33
	v_or_b32_e32 v98, s19, v90
	s_addc_u32 s11, s14, s11
	v_mul_f32_e32 v32, v33, v32
	v_lshl_add_u64 v[96:97], s[10:11], 0, v[64:65]
	v_cvt_pk_bf16_f32 v31, v31, v32
	v_lshlrev_b32_e32 v32, 1, v98
	v_mov_b32_e32 v33, v1
	v_lshl_add_u64 v[88:89], v[96:97], 0, v[32:33]
	v_mov_b32_e32 v102, v30
	v_mov_b32_e32 v103, v31
	v_lshlrev_b32_e32 v30, 16, v86
	v_add_f32_e32 v26, v95, v26
	v_mul_f32_e32 v26, v26, v30
	v_and_b32_e32 v30, 0xffff0000, v86
	v_add_f32_e32 v27, v95, v27
	v_mul_f32_e32 v27, v27, v30
	v_cvt_pk_bf16_f32 v26, v26, v27
	v_lshlrev_b32_e32 v27, 16, v87
	v_add_f32_e32 v28, v95, v28
	v_mul_f32_e32 v27, v28, v27
	v_and_b32_e32 v28, 0xffff0000, v87
	v_add_f32_e32 v29, v95, v29
	v_mul_f32_e32 v28, v29, v28
	v_cvt_pk_bf16_f32 v27, v27, v28
	v_lshlrev_b32_e32 v28, 16, v84
	v_add_f32_e32 v22, v94, v22
	v_mul_f32_e32 v22, v22, v28
	v_and_b32_e32 v28, 0xffff0000, v84
	v_add_f32_e32 v23, v94, v23
	v_mul_f32_e32 v23, v23, v28
	v_mov_b32_e32 v104, v26
	v_mov_b32_e32 v105, v27
	s_nop 1
	v_permlane16_swap_b32_e32 v102, v104
	v_permlane16_swap_b32_e32 v103, v105
	global_store_dwordx4 v[88:89], v[102:105], off
	v_cvt_pk_bf16_f32 v22, v22, v23
	v_lshlrev_b32_e32 v23, 16, v85
	v_add_f32_e32 v24, v94, v24
	v_mul_f32_e32 v23, v24, v23
	v_and_b32_e32 v24, 0xffff0000, v85
	v_add_f32_e32 v25, v94, v25
	v_lshl_add_u64 v[26:27], s[10:11], 0, v[66:67]
	v_mul_f32_e32 v24, v25, v24
	v_cvt_pk_bf16_f32 v23, v23, v24
	v_lshl_add_u64 v[24:25], v[26:27], 0, v[32:33]
	v_mov_b32_e32 v106, v22
	v_mov_b32_e32 v107, v23
	v_lshlrev_b32_e32 v22, 16, v82
	v_add_f32_e32 v18, v94, v18
	v_mul_f32_e32 v18, v18, v22
	v_and_b32_e32 v22, 0xffff0000, v82
	v_add_f32_e32 v19, v94, v19
	v_mul_f32_e32 v19, v19, v22
	v_cvt_pk_bf16_f32 v18, v18, v19
	v_lshlrev_b32_e32 v19, 16, v83
	v_add_f32_e32 v20, v94, v20
	v_mul_f32_e32 v19, v20, v19
	v_and_b32_e32 v20, 0xffff0000, v83
	v_add_f32_e32 v21, v94, v21
	v_mul_f32_e32 v20, v21, v20
	v_cvt_pk_bf16_f32 v19, v19, v20
	v_lshlrev_b32_e32 v20, 16, v80
	v_add_f32_e32 v14, v93, v14
	v_mul_f32_e32 v14, v14, v20
	v_and_b32_e32 v20, 0xffff0000, v80
	v_add_f32_e32 v15, v93, v15
	v_mul_f32_e32 v15, v15, v20
	v_mov_b32_e32 v108, v18
	v_mov_b32_e32 v109, v19
	s_nop 1
	v_permlane16_swap_b32_e32 v106, v108
	v_permlane16_swap_b32_e32 v107, v109
	global_store_dwordx4 v[24:25], v[106:109], off
	v_cvt_pk_bf16_f32 v14, v14, v15
	v_lshlrev_b32_e32 v15, 16, v81
	v_add_f32_e32 v16, v93, v16
	v_mul_f32_e32 v15, v16, v15
	v_and_b32_e32 v16, 0xffff0000, v81
	v_add_f32_e32 v17, v93, v17
	v_lshl_add_u64 v[18:19], s[10:11], 0, v[68:69]
	v_mul_f32_e32 v16, v17, v16
	v_cvt_pk_bf16_f32 v15, v15, v16
	v_lshl_add_u64 v[16:17], v[18:19], 0, v[32:33]
	v_mov_b32_e32 v110, v14
	v_mov_b32_e32 v111, v15
	v_lshlrev_b32_e32 v14, 16, v78
	v_add_f32_e32 v10, v93, v10
	v_mul_f32_e32 v10, v10, v14
	v_and_b32_e32 v14, 0xffff0000, v78
	v_add_f32_e32 v11, v93, v11
	v_mul_f32_e32 v11, v11, v14
	v_cvt_pk_bf16_f32 v10, v10, v11
	v_lshlrev_b32_e32 v11, 16, v79
	v_add_f32_e32 v12, v93, v12
	v_mul_f32_e32 v11, v12, v11
	v_and_b32_e32 v12, 0xffff0000, v79
	v_add_f32_e32 v13, v93, v13
	v_mul_f32_e32 v12, v13, v12
	v_cvt_pk_bf16_f32 v11, v11, v12
	v_lshlrev_b32_e32 v12, 16, v76
	v_add_f32_e32 v6, v73, v6
	v_mul_f32_e32 v6, v6, v12
	v_and_b32_e32 v12, 0xffff0000, v76
	v_add_f32_e32 v7, v73, v7
	v_mul_f32_e32 v7, v7, v12
	v_mov_b32_e32 v112, v10
	v_mov_b32_e32 v113, v11
	s_nop 1
	v_permlane16_swap_b32_e32 v110, v112
	v_permlane16_swap_b32_e32 v111, v113
	global_store_dwordx4 v[16:17], v[110:113], off
	v_cvt_pk_bf16_f32 v6, v6, v7
	v_lshlrev_b32_e32 v7, 16, v77
	v_add_f32_e32 v8, v73, v8
	v_mul_f32_e32 v7, v8, v7
	v_and_b32_e32 v8, 0xffff0000, v77
	v_add_f32_e32 v9, v73, v9
	v_lshl_add_u64 v[10:11], s[10:11], 0, v[70:71]
	v_mul_f32_e32 v8, v9, v8
	v_cvt_pk_bf16_f32 v7, v7, v8
	v_lshl_add_u64 v[8:9], v[10:11], 0, v[32:33]
	v_mov_b32_e32 v114, v6
	v_mov_b32_e32 v115, v7
	v_lshlrev_b32_e32 v6, 16, v74
	v_add_f32_e32 v2, v73, v2
	v_mul_f32_e32 v2, v2, v6
	v_and_b32_e32 v6, 0xffff0000, v74
	v_add_f32_e32 v3, v73, v3
	v_mul_f32_e32 v3, v3, v6
	v_cvt_pk_bf16_f32 v2, v2, v3
	v_lshlrev_b32_e32 v3, 16, v75
	v_add_f32_e32 v4, v73, v4
	s_add_i32 s4, s4, s15
	v_mul_f32_e32 v3, v4, v3
	v_and_b32_e32 v4, 0xffff0000, v75
	v_add_f32_e32 v5, v73, v5
	s_cmpk_gt_i32 s4, 0xff
	v_mul_f32_e32 v4, v5, v4
	v_cvt_pk_bf16_f32 v3, v3, v4
	v_mov_b32_e32 v116, v2
	v_mov_b32_e32 v117, v3
	s_nop 1
	v_permlane16_swap_b32_e32 v114, v116
	v_permlane16_swap_b32_e32 v115, v117
	global_store_dwordx4 v[8:9], v[114:117], off
	s_waitcnt lgkmcnt(0)
	s_barrier
	s_cbranch_scc0 .LBB0_797
